# second row-norm loop: both rows' loads prefetched one iteration ahead into a register bank
# baseline (speedup 1.0000x reference)
; __device__ __forceinline__ int otid() { int t = threadIdx.x; asm volatile("" : "+v"(t)); return t; }
; __device__ __forceinline__ int obid() { int t = blockIdx.x; asm volatile("" : "+s"(t)); return t; }
; template <bool FINAL>
; __device__ void phase_norm(const float* __restrict__ x, const float* __restrict__ g, bf16_t* __restrict__ xb, float* __restrict__ ss_out, float* __restrict__ outf, int b0, int nb, int rbeg, int rend) {
;     const int tid_ = otid(), lane = tid_ & 63, wid = tid_ >> 6; const int bq = obid() - b0;
;     if (bq < 0) return;
;     f32x4 gv[4];
; #pragma unroll
;     for (int i = 0; i < 4; ++i) gv[i] = FINAL ? *(const f32x4*)(g + (lane + 64 * i) * 4) : (f32x4){1.f, 1.f, 1.f, 1.f};
;     for (int row0 = rbeg + bq * 8 + wid; row0 < rend; row0 += nb * 16) {
;         const int row1 = row0 + nb * 8; const bool has1 = row1 < rend;
;         const float* xr0 = x + (size_t)row0 * 1024; const float* xr1 = x + (size_t)(has1 ? row1 : row0) * 1024; f32x4 v[4], u[4]; float ss = 0.f, st = 0.f;
; #pragma unroll
;         for (int i = 0; i < 4; ++i) { v[i] = *(const f32x4*)(xr0 + (lane + 64 * i) * 4); u[i] = *(const f32x4*)(xr1 + (lane + 64 * i) * 4); }
.LBB0_629:
	s_or_b64 exec, exec, s[14:15]
	v_mov_b32_e32 v0, v191
	s_mov_b32 s10, s2
	s_cmpk_lt_i32 s10, 0x80
	s_cbranch_scc1 .LBB0_640
	v_ashrrev_i32_e32 v1, 6, v0
	v_lshl_add_u32 v1, s10, 3, v1
	v_add_u32_e32 v32, 0x9c00, v1
	v_cmp_gt_i32_e32 vcc, s54, v32
	s_and_saveexec_b64 s[12:13], vcc
	s_cbranch_execz .LBB0_639
	v_and_b32_e32 v1, 64, v226
	v_add_u32_e32 v2, 64, v1
	v_xor_b32_e32 v3, 32, v226
	v_cmp_lt_i32_e32 vcc, v3, v2
	s_load_dwordx2 s[16:17], s[0:1], 0x0
	v_and_b32_e32 v4, 63, v0
	v_cndmask_b32_e32 v3, v226, v3, vcc
	v_lshlrev_b32_e32 v48, 2, v3
	v_xor_b32_e32 v3, 16, v226
	v_cmp_lt_i32_e32 vcc, v3, v2
	v_readlane_b32 s10, v254, 62
	v_ashrrev_i32_e32 v33, 31, v32
	v_cndmask_b32_e32 v3, v226, v3, vcc
	v_lshlrev_b32_e32 v49, 2, v3
	v_xor_b32_e32 v3, 8, v226
	v_cmp_lt_i32_e32 vcc, v3, v2
	v_lshlrev_b32_e32 v0, 2, v4
	v_cmp_gt_u32_e64 s[40:41], 16, v4
	v_cndmask_b32_e32 v3, v226, v3, vcc
	v_lshlrev_b32_e32 v50, 2, v3
	v_xor_b32_e32 v3, 4, v226
	v_cmp_lt_i32_e32 vcc, v3, v2
	v_mov_b32_e32 v1, v184
	v_readlane_b32 s11, v254, 63
	v_cndmask_b32_e32 v3, v226, v3, vcc
	v_lshlrev_b32_e32 v51, 2, v3
	v_xor_b32_e32 v3, 2, v226
	v_cmp_lt_i32_e32 vcc, v3, v2
	v_cmp_eq_u32_e64 s[42:43], 0, v4
	v_mov_b32_e32 v5, v184
	v_cndmask_b32_e32 v3, v226, v3, vcc
	v_lshlrev_b32_e32 v52, 2, v3
	v_xor_b32_e32 v3, 1, v226
	v_cmp_lt_i32_e32 vcc, v3, v2
	v_lshlrev_b64 v[6:7], 6, v[32:33]
	v_lshl_add_u64 v[34:35], s[10:11], 0, v[0:1]
	v_cndmask_b32_e32 v2, v226, v3, vcc
	v_lshlrev_b32_e32 v53, 2, v2
	v_lshlrev_b32_e32 v2, 4, v4
	v_lshlrev_b32_e32 v4, 3, v4
	v_lshl_add_u64 v[38:39], s[8:9], 0, v[4:5]
	v_lshl_add_u64 v[0:1], v[6:7], 0, v[0:1]
	s_mov_b64 s[8:9], 0x3e600000
	s_lshl_b32 s10, s25, 4
	v_lshl_add_u64 v[40:41], v[0:1], 0, s[8:9]
	v_lshlrev_b64 v[0:1], 12, v[32:33]
	v_mov_b32_e32 v3, v184
	s_ashr_i32 s11, s10, 31
	v_lshlrev_b64 v[42:43], 11, v[32:33]
	v_or_b32_e32 v0, v0, v2
	s_waitcnt lgkmcnt(0)
	v_lshl_add_u64 v[36:37], s[16:17], 0, v[2:3]
	s_lshl_b64 s[8:9], s[10:11], 6
	v_or_b32_e32 v42, v42, v4
	s_lshl_b64 s[14:15], s[10:11], 11
	s_lshl_b32 s26, s26, 3
	v_lshl_add_u64 v[44:45], s[16:17], 0, v[0:1]
	s_lshl_b64 s[16:17], s[10:11], 12
	s_mov_b64 s[18:19], 0
	global_load_dwordx4 v[88:91], v[44:45], off
	global_load_dwordx4 v[84:87], v[44:45], off offset:1024
	global_load_dwordx4 v[80:83], v[44:45], off offset:2048
	global_load_dwordx4 v[76:79], v[44:45], off offset:3072
	v_add_u32_e32 v95, s26, v32
	v_add_u32_e32 v95, 0xfffffc00, v95
	v_cmp_gt_i32_e32 vcc, s54, v95
	s_nop 1
	v_cndmask_b32_e32 v94, v32, v95, vcc
	v_ashrrev_i32_e32 v95, 31, v94
	v_lshlrev_b64 v[94:95], 12, v[94:95]
	v_lshl_add_u64 v[94:95], v[36:37], 0, v[94:95]
	global_load_dwordx4 v[72:75], v[94:95], off
	global_load_dwordx4 v[68:71], v[94:95], off offset:1024
	global_load_dwordx4 v[64:67], v[94:95], off offset:2048
	global_load_dwordx4 v[60:63], v[94:95], off offset:3072
	s_waitcnt vmcnt(0)
	s_branch .LBB0_634

; __device__ __forceinline__ unsigned pack2(float lo, float hi) { const f32x2_t v = {lo, hi}; const bf16x2_t b = __builtin_convertvector(v, bf16x2_t); return __builtin_bit_cast(unsigned, b); }
; template <bool FINAL>
; __device__ void phase_norm(const float* __restrict__ x, const float* __restrict__ g, bf16_t* __restrict__ xb, float* __restrict__ ss_out, float* __restrict__ outf, int b0, int nb, int rbeg, int rend) {
;     ...
;     for (int row0 = rbeg + bq * 8 + wid; row0 < rend; row0 += nb * 16) {
;         const int row1 = row0 + nb * 8; const bool has1 = row1 < rend;
;         const float* xr0 = x + (size_t)row0 * 1024; const float* xr1 = x + (size_t)(has1 ? row1 : row0) * 1024; f32x4 v[4], u[4]; float ss = 0.f, st = 0.f;
; #pragma unroll
;         for (int i = 0; i < 4; ++i) { v[i] = *(const f32x4*)(xr0 + (lane + 64 * i) * 4); u[i] = *(const f32x4*)(xr1 + (lane + 64 * i) * 4); }
; #pragma unroll
;         for (int i = 0; i < 4; ++i) { ss += v[i][0] * v[i][0] + v[i][1] * v[i][1] + v[i][2] * v[i][2] + v[i][3] * v[i][3]; st += u[i][0] * u[i][0] + u[i][1] * u[i][1] + u[i][2] * u[i][2] + u[i][3] * u[i][3]; }
; #pragma unroll
;         for (int o = 32; o > 0; o >>= 1) { ss += __shfl_xor(ss, o); st += __shfl_xor(st, o); }
; #pragma unroll
;         for (int rr = 0; rr < 2; ++rr) { if (rr == 1 && !has1) break; const int row = rr ? row1 : row0; const float sv = rr ? st : ss;
;             if (FINAL) { const float rstd = rsqrtf(sv * (1.0f / 1024.0f) + 1e-6f);
; #pragma unroll
;                 for (int i = 0; i < 4; ++i) *(f32x4*)(outf + (size_t)row * 1024 + (lane + 64 * i) * 4) = (rr ? u[i] : v[i]) * rstd * gv[i]; }
;             else { if (lane < 16) ss_out[(size_t)row * 16 + lane] = lane == 0 ? sv : 0.f;
; #pragma unroll
;                 for (int i = 0; i < 4; ++i) { const f32x4 y = rr ? u[i] : v[i]; uint2 w; w.x = pack2(y[0], y[1]); w.y = pack2(y[2], y[3]); *(uint2*)(xb + (size_t)row * 1024 + (lane + 64 * i) * 4) = w; } } }
.LBB0_634:
	v_add_u32_e32 v0, s26, v32
	v_add_u32_e32 v46, 0xfffffc00, v0
	v_cmp_gt_i32_e64 s[44:45], s54, v46
	s_waitcnt vmcnt(4)
	v_mov_b64_e32 v[28:29], v[88:89]
	v_mov_b64_e32 v[30:31], v[90:91]
	v_mov_b64_e32 v[24:25], v[84:85]
	v_mov_b64_e32 v[26:27], v[86:87]
	v_mov_b64_e32 v[20:21], v[80:81]
	v_mov_b64_e32 v[22:23], v[82:83]
	v_mov_b64_e32 v[16:17], v[76:77]
	v_mov_b64_e32 v[18:19], v[78:79]
	v_mov_b64_e32 v[12:13], v[72:73]
	v_mov_b64_e32 v[14:15], v[74:75]
	v_mov_b64_e32 v[8:9], v[68:69]
	v_mov_b64_e32 v[10:11], v[70:71]
	v_mov_b64_e32 v[4:5], v[64:65]
	v_mov_b64_e32 v[6:7], v[66:67]
	v_mul_f32_e32 v33, v29, v29
	v_cndmask_b32_e64 v0, v32, v46, s[44:45]
	v_ashrrev_i32_e32 v1, 31, v0
	v_lshlrev_b64 v[0:1], 12, v[0:1]
	v_lshl_add_u64 v[0:1], v[36:37], 0, v[0:1]
	s_nop 0
	v_mov_b64_e32 v[0:1], v[60:61]
	v_mov_b64_e32 v[2:3], v[62:63]
	v_add_u32_e32 v93, s10, v32
	v_cmp_ge_i32_e32 vcc, s55, v93
	s_and_saveexec_b64 s[22:23], vcc
	v_lshl_add_u64 v[96:97], v[44:45], 0, s[16:17]
	global_load_dwordx4 v[88:91], v[96:97], off
	global_load_dwordx4 v[84:87], v[96:97], off offset:1024
	global_load_dwordx4 v[80:83], v[96:97], off offset:2048
	global_load_dwordx4 v[76:79], v[96:97], off offset:3072
	v_add_u32_e32 v95, s26, v93
	v_add_u32_e32 v95, 0xfffffc00, v95
	v_cmp_gt_i32_e32 vcc, s54, v95
	s_nop 1
	v_cndmask_b32_e32 v94, v93, v95, vcc
	v_ashrrev_i32_e32 v95, 31, v94
	v_lshlrev_b64 v[94:95], 12, v[94:95]
	v_lshl_add_u64 v[94:95], v[36:37], 0, v[94:95]
	global_load_dwordx4 v[72:75], v[94:95], off
	global_load_dwordx4 v[68:71], v[94:95], off offset:1024
	global_load_dwordx4 v[64:67], v[94:95], off offset:2048
	global_load_dwordx4 v[60:63], v[94:95], off offset:3072
	s_or_b64 exec, exec, s[22:23]
	v_mul_f32_e32 v47, v25, v25
	s_waitcnt lgkmcnt(0)
	v_mul_f32_e32 v54, v21, v21
	v_fmac_f32_e32 v33, v28, v28
	v_fmac_f32_e32 v47, v24, v24
	v_fmac_f32_e32 v54, v20, v20
	v_fmac_f32_e32 v33, v30, v30
	v_fmac_f32_e32 v47, v26, v26
	v_mul_f32_e32 v55, v17, v17
	v_fmac_f32_e32 v54, v22, v22
	v_fmac_f32_e32 v33, v31, v31
	v_fmac_f32_e32 v47, v27, v27
	v_fmac_f32_e32 v55, v16, v16
	v_fmac_f32_e32 v54, v23, v23
	v_add_f32_e32 v33, v33, v47
	v_fmac_f32_e32 v55, v18, v18
	v_add_f32_e32 v33, v33, v54
	v_fmac_f32_e32 v55, v19, v19
	v_add_f32_e32 v33, v33, v55
	ds_bpermute_b32 v57, v48, v33
	s_waitcnt lgkmcnt(0)
	v_add_f32_e32 v33, v33, v57
	s_nop 0
	v_mul_f32_e32 v47, v13, v13
	s_nop 0
	v_mul_f32_e32 v54, v9, v9
	s_nop 0
	v_mul_f32_e32 v56, v5, v5
	v_fmac_f32_e32 v47, v12, v12
	v_fmac_f32_e32 v54, v8, v8
	s_nop 0
	v_mul_f32_e32 v55, v1, v1
	v_fmac_f32_e32 v56, v4, v4
	v_fmac_f32_e32 v47, v14, v14
	v_fmac_f32_e32 v54, v10, v10
	v_fmac_f32_e32 v55, v0, v0
	v_fmac_f32_e32 v56, v6, v6
	v_fmac_f32_e32 v47, v15, v15
	v_fmac_f32_e32 v54, v11, v11
	v_fmac_f32_e32 v55, v2, v2
	v_fmac_f32_e32 v56, v7, v7
	v_add_f32_e32 v47, v47, v54
	v_fmac_f32_e32 v55, v3, v3
	v_add_f32_e32 v47, v47, v56
	v_add_f32_e32 v47, v47, v55
	ds_bpermute_b32 v54, v48, v47
	ds_bpermute_b32 v55, v49, v33
	s_waitcnt lgkmcnt(1)
	v_add_f32_e32 v47, v47, v54
	ds_bpermute_b32 v54, v49, v47
	s_waitcnt lgkmcnt(1)
	v_add_f32_e32 v33, v33, v55
	ds_bpermute_b32 v55, v50, v33
	s_waitcnt lgkmcnt(1)
	v_add_f32_e32 v47, v47, v54
	ds_bpermute_b32 v54, v50, v47
	s_waitcnt lgkmcnt(1)
	v_add_f32_e32 v33, v33, v55
	ds_bpermute_b32 v55, v51, v33
	s_waitcnt lgkmcnt(1)
	v_add_f32_e32 v47, v47, v54
	ds_bpermute_b32 v54, v51, v47
	s_waitcnt lgkmcnt(1)
	v_add_f32_e32 v33, v33, v55
	ds_bpermute_b32 v55, v52, v33
	s_waitcnt lgkmcnt(1)
	v_add_f32_e32 v54, v47, v54
	ds_bpermute_b32 v56, v52, v54
	s_waitcnt lgkmcnt(1)
	v_add_f32_e32 v47, v33, v55
	ds_bpermute_b32 v55, v53, v47
	s_waitcnt lgkmcnt(1)
	v_add_f32_e32 v33, v54, v56
	ds_bpermute_b32 v54, v53, v33
	s_and_saveexec_b64 s[20:21], s[40:41]
	s_cbranch_execz .LBB0_636
	s_waitcnt lgkmcnt(1)
	v_add_f32_e32 v47, v47, v55
	v_lshl_add_u64 v[56:57], s[94:95], 0, v[40:41]
	v_cndmask_b32_e64 v47, 0, v47, s[42:43]
	global_store_dword v[56:57], v47, off
